# diff-attention unit epilogue: the two lane-xor-32 exchanges done with v_permlane32_swap plus a select instead of ds_bpermute round trips
# baseline (speedup 1.0000x reference)
; #define ATT_LAS __attribute__((address_space(3)))
; __device__ __forceinline__ void diff_unit(ATT_LAS unsigned char* lds, int b, int h, int qb, const bf16_t* __restrict__ DQ, const bf16_t* __restrict__ DK, const bf16_t* __restrict__ VT,
;                                           float lam, const float* __restrict__ gout, bf16_t* __restrict__ MIXED) {
;     ...
;     __syncthreads();
;     lsum += __shfl_xor(lsum, 32);
;     const float inv = 1.0f / lsum;
;     ATT_LAS float* X = (ATT_LAS float*)lds;
;     if (comp == 1) { const float f = inv * lam;
; #pragma unroll
;         for (int e = 0; e < 4; ++e)
; #pragma unroll
;             for (int i = 0; i < 16; ++i) X[((wq * 4 + e) * 16 + i) * 64 + lane] = O[e][i] * f; }
;     __syncthreads();
;     if (comp == 0) {
;         float ss = 0.f;
; #pragma unroll
;         for (int e = 0; e < 4; ++e)
; #pragma unroll
;             for (int i = 0; i < 16; ++i) { const float o = O[e][i] * inv - X[((wq * 4 + e) * 16 + i) * 64 + lane]; O[e][i] = o; ss += o * o; }
.LBB0_556:
	s_mov_b32 s98, -1
	s_mov_b32 s99, 0
	v_mov_b32_e32 v1, v161
	v_mov_b32_e32 v252, v161
	s_nop 1
	v_permlane32_swap_b32_e32 v1, v252
	v_cndmask_b32_e64 v1, v1, v252, s[98:99]
	s_cmp_lg_u32 s41, 1
	s_waitcnt lgkmcnt(0)
	s_barrier
	v_add_f32_e32 v1, v161, v1
	v_div_scale_f32 v2, s[22:23], v1, v1, 1.0
	v_rcp_f32_e32 v3, v2
	v_div_scale_f32 v4, vcc, 1.0, v1, 1.0
	v_fma_f32 v5, -v2, v3, 1.0
	v_fmac_f32_e32 v3, v5, v3
	v_mul_f32_e32 v5, v4, v3
	v_fma_f32 v6, -v2, v5, v4
	v_fmac_f32_e32 v5, v6, v3
	v_fma_f32 v2, -v2, v5, v4
	v_div_fmas_f32 v2, v2, v3, v5
	v_div_fixup_f32 v2, v2, v1, 1.0
	s_cbranch_scc1 .LBB0_558
	v_mul_f32_e32 v1, v189, v2
	v_mul_f32_e32 v3, v64, v1
	v_lshl_add_u32 v4, s39, 14, v197
	v_mul_f32_e32 v5, v65, v1
	ds_write2st64_b32 v4, v3, v5 offset1:1
	v_mul_f32_e32 v3, v66, v1
	v_mul_f32_e32 v5, v67, v1
	ds_write2st64_b32 v4, v3, v5 offset0:2 offset1:3
	v_mul_f32_e32 v3, v68, v1
	v_mul_f32_e32 v5, v69, v1
	ds_write2st64_b32 v4, v3, v5 offset0:4 offset1:5
	v_mul_f32_e32 v3, v70, v1
	v_mul_f32_e32 v5, v71, v1
	ds_write2st64_b32 v4, v3, v5 offset0:6 offset1:7
	v_mul_f32_e32 v3, v72, v1
	v_mul_f32_e32 v5, v73, v1
	ds_write2st64_b32 v4, v3, v5 offset0:8 offset1:9
	v_mul_f32_e32 v3, v74, v1
	v_mul_f32_e32 v5, v75, v1
	ds_write2st64_b32 v4, v3, v5 offset0:10 offset1:11
	v_mul_f32_e32 v3, v76, v1
	v_mul_f32_e32 v5, v77, v1
	ds_write2st64_b32 v4, v3, v5 offset0:12 offset1:13
	v_mul_f32_e32 v3, v78, v1
	v_mul_f32_e32 v5, v79, v1
	ds_write2st64_b32 v4, v3, v5 offset0:14 offset1:15
	v_mul_f32_e32 v3, v48, v1
	v_mul_f32_e32 v5, v49, v1
	ds_write2st64_b32 v4, v3, v5 offset0:16 offset1:17
	v_mul_f32_e32 v3, v50, v1
	v_mul_f32_e32 v5, v51, v1
	ds_write2st64_b32 v4, v3, v5 offset0:18 offset1:19
	v_mul_f32_e32 v3, v52, v1
	v_mul_f32_e32 v5, v53, v1
	ds_write2st64_b32 v4, v3, v5 offset0:20 offset1:21
	v_mul_f32_e32 v3, v54, v1
	v_mul_f32_e32 v5, v55, v1
	ds_write2st64_b32 v4, v3, v5 offset0:22 offset1:23
	v_mul_f32_e32 v3, v56, v1
	v_mul_f32_e32 v5, v57, v1
	ds_write2st64_b32 v4, v3, v5 offset0:24 offset1:25
	v_mul_f32_e32 v3, v58, v1
	v_mul_f32_e32 v5, v59, v1
	ds_write2st64_b32 v4, v3, v5 offset0:26 offset1:27
	v_mul_f32_e32 v3, v60, v1
	v_mul_f32_e32 v5, v61, v1
	ds_write2st64_b32 v4, v3, v5 offset0:28 offset1:29
	v_mul_f32_e32 v3, v62, v1
	v_mul_f32_e32 v5, v63, v1
	ds_write2st64_b32 v4, v3, v5 offset0:30 offset1:31
	v_mul_f32_e32 v3, v32, v1
	v_mul_f32_e32 v5, v33, v1
	ds_write2st64_b32 v4, v3, v5 offset0:32 offset1:33
	v_mul_f32_e32 v3, v34, v1
	v_mul_f32_e32 v5, v35, v1
	ds_write2st64_b32 v4, v3, v5 offset0:34 offset1:35
	v_mul_f32_e32 v3, v36, v1
	v_mul_f32_e32 v5, v37, v1
	ds_write2st64_b32 v4, v3, v5 offset0:36 offset1:37
	v_mul_f32_e32 v3, v38, v1
	v_mul_f32_e32 v5, v39, v1
	ds_write2st64_b32 v4, v3, v5 offset0:38 offset1:39
	v_mul_f32_e32 v3, v40, v1
	v_mul_f32_e32 v5, v41, v1
	ds_write2st64_b32 v4, v3, v5 offset0:40 offset1:41
	v_mul_f32_e32 v3, v42, v1
	v_mul_f32_e32 v5, v43, v1
	ds_write2st64_b32 v4, v3, v5 offset0:42 offset1:43
	v_mul_f32_e32 v3, v44, v1
	v_mul_f32_e32 v5, v45, v1
	ds_write2st64_b32 v4, v3, v5 offset0:44 offset1:45
	v_mul_f32_e32 v3, v46, v1
	v_mul_f32_e32 v5, v47, v1
	ds_write2st64_b32 v4, v3, v5 offset0:46 offset1:47
	v_mul_f32_e32 v3, v16, v1
	v_mul_f32_e32 v5, v17, v1
	ds_write2st64_b32 v4, v3, v5 offset0:48 offset1:49
	v_mul_f32_e32 v3, v18, v1
	v_mul_f32_e32 v5, v19, v1
	ds_write2st64_b32 v4, v3, v5 offset0:50 offset1:51
	v_mul_f32_e32 v3, v20, v1
	v_mul_f32_e32 v5, v21, v1
	ds_write2st64_b32 v4, v3, v5 offset0:52 offset1:53
	v_mul_f32_e32 v3, v22, v1
	v_mul_f32_e32 v5, v23, v1
	ds_write2st64_b32 v4, v3, v5 offset0:54 offset1:55
	v_mul_f32_e32 v3, v24, v1
	v_mul_f32_e32 v5, v25, v1
	ds_write2st64_b32 v4, v3, v5 offset0:56 offset1:57
	v_mul_f32_e32 v3, v26, v1
	v_mul_f32_e32 v5, v27, v1
	ds_write2st64_b32 v4, v3, v5 offset0:58 offset1:59
	v_mul_f32_e32 v3, v28, v1
	v_mul_f32_e32 v5, v29, v1
	ds_write2st64_b32 v4, v3, v5 offset0:60 offset1:61
	v_mul_f32_e32 v3, v30, v1
	v_mul_f32_e32 v1, v31, v1
	ds_write2st64_b32 v4, v3, v1 offset0:62 offset1:63
.LBB0_558:
	s_cmpk_gt_u32 s40, 0xff
	s_waitcnt lgkmcnt(0)
	s_barrier
	s_cbranch_scc1 .LBB0_527
	s_lshl_b32 s4, s40, 8
	s_and_b32 s22, s4, 0xc000
	v_add_u32_e32 v1, s22, v197
	ds_read2st64_b32 v[4:5], v1 offset1:1
	ds_read2st64_b32 v[6:7], v1 offset0:2 offset1:3
	ds_read2st64_b32 v[8:9], v1 offset0:4 offset1:5
	ds_read2st64_b32 v[10:11], v1 offset0:6 offset1:7
	s_or_b32 s4, s4, 0x3f00
	s_waitcnt lgkmcnt(3)
	v_fma_f32 v64, v64, v2, -v4
	v_fma_f32 v65, v65, v2, -v5
	s_waitcnt lgkmcnt(2)
	v_fma_f32 v66, v66, v2, -v6
	v_fma_f32 v67, v67, v2, -v7
	s_waitcnt lgkmcnt(1)
	v_fma_f32 v68, v68, v2, -v8
	v_fma_f32 v69, v69, v2, -v9
	s_waitcnt lgkmcnt(0)
	v_fma_f32 v70, v70, v2, -v10
	v_fma_f32 v71, v71, v2, -v11
	ds_read2st64_b32 v[4:5], v1 offset0:8 offset1:9
	ds_read2st64_b32 v[6:7], v1 offset0:10 offset1:11
	ds_read2st64_b32 v[8:9], v1 offset0:12 offset1:13
	ds_read2st64_b32 v[10:11], v1 offset0:14 offset1:15
	v_mul_f32_e32 v3, v65, v65
	v_fmac_f32_e32 v3, v64, v64
	s_waitcnt lgkmcnt(2)
	v_fma_f32 v74, v74, v2, -v6
	v_fma_f32 v72, v72, v2, -v4
	v_fma_f32 v73, v73, v2, -v5
	v_fma_f32 v75, v75, v2, -v7
	s_waitcnt lgkmcnt(1)
	v_fma_f32 v76, v76, v2, -v8
	v_fma_f32 v77, v77, v2, -v9
	s_waitcnt lgkmcnt(0)
	v_fma_f32 v78, v78, v2, -v10
	v_fma_f32 v79, v79, v2, -v11
	ds_read2st64_b32 v[4:5], v1 offset0:16 offset1:17
	ds_read2st64_b32 v[6:7], v1 offset0:18 offset1:19
	ds_read2st64_b32 v[8:9], v1 offset0:20 offset1:21
	ds_read2st64_b32 v[10:11], v1 offset0:22 offset1:23
	v_fmac_f32_e32 v3, v66, v66
	v_fmac_f32_e32 v3, v67, v67
	s_waitcnt lgkmcnt(2)
; #define ATT_LAS __attribute__((address_space(3)))
; __device__ __forceinline__ void diff_unit(ATT_LAS unsigned char* lds, int b, int h, int qb, const bf16_t* __restrict__ DQ, const bf16_t* __restrict__ DK, const bf16_t* __restrict__ VT,
;                                           float lam, const float* __restrict__ gout, bf16_t* __restrict__ MIXED) {
;     ...
;         for (int e = 0; e < 4; ++e)
; #pragma unroll
;             for (int i = 0; i < 16; ++i) { const float o = O[e][i] * inv - X[((wq * 4 + e) * 16 + i) * 64 + lane]; O[e][i] = o; ss += o * o; }
;         ss += __shfl_xor(ss, 32);
;         const float rstd = rsqrtf(ss * (1.0f / 128.0f) + EPS) * 0.8f;
;         ATT_LAS unsigned char* stg = lds + 65536 + wq * OSTG_BYTES;
; #pragma unroll
;         for (int e = 0; e < 4; ++e)
; #pragma unroll
;             for (int g4 = 0; g4 < 4; ++g4) { const int e0 = 32 * e + 8 * g4 + 4 * hh; const f32x4 g = *(const f32x4*)(gout + e0);
	v_fma_f32 v50, v50, v2, -v6
	v_fma_f32 v48, v48, v2, -v4
	v_fma_f32 v49, v49, v2, -v5
	v_fma_f32 v51, v51, v2, -v7
	s_waitcnt lgkmcnt(1)
	v_fma_f32 v52, v52, v2, -v8
	v_fma_f32 v53, v53, v2, -v9
	s_waitcnt lgkmcnt(0)
	v_fma_f32 v54, v54, v2, -v10
	v_fma_f32 v55, v55, v2, -v11
	ds_read2st64_b32 v[4:5], v1 offset0:24 offset1:25
	ds_read2st64_b32 v[6:7], v1 offset0:26 offset1:27
	ds_read2st64_b32 v[8:9], v1 offset0:28 offset1:29
	ds_read2st64_b32 v[10:11], v1 offset0:30 offset1:31
	v_fmac_f32_e32 v3, v68, v68
	v_fmac_f32_e32 v3, v69, v69
	v_fmac_f32_e32 v3, v70, v70
	v_fmac_f32_e32 v3, v71, v71
	v_fmac_f32_e32 v3, v72, v72
	s_waitcnt lgkmcnt(3)
	v_fma_f32 v56, v56, v2, -v4
	v_fma_f32 v57, v57, v2, -v5
	s_waitcnt lgkmcnt(2)
	v_fma_f32 v58, v58, v2, -v6
	v_fma_f32 v59, v59, v2, -v7
	s_waitcnt lgkmcnt(1)
	v_fma_f32 v60, v60, v2, -v8
	v_fma_f32 v61, v61, v2, -v9
	s_waitcnt lgkmcnt(0)
	v_fma_f32 v62, v62, v2, -v10
	v_fma_f32 v63, v63, v2, -v11
	ds_read2st64_b32 v[4:5], v1 offset0:32 offset1:33
	ds_read2st64_b32 v[6:7], v1 offset0:34 offset1:35
	ds_read2st64_b32 v[8:9], v1 offset0:36 offset1:37
	ds_read2st64_b32 v[10:11], v1 offset0:38 offset1:39
	global_load_dwordx4 v[112:115], v[158:159], off
	global_load_dwordx4 v[116:119], v[158:159], off offset:32
	global_load_dwordx4 v[120:123], v[158:159], off offset:64
	global_load_dwordx4 v[124:127], v[158:159], off offset:96
	global_load_dwordx4 v[128:131], v[158:159], off offset:128
	global_load_dwordx4 v[132:135], v[158:159], off offset:160
	global_load_dwordx4 v[136:139], v[158:159], off offset:192
	global_load_dwordx4 v[140:143], v[158:159], off offset:224
	global_load_dwordx4 v[218:221], v[158:159], off offset:256
	global_load_dwordx4 v[222:225], v[158:159], off offset:288
	global_load_dwordx4 v[226:229], v[158:159], off offset:320
	global_load_dwordx4 v[230:233], v[158:159], off offset:352
	global_load_dwordx4 v[234:237], v[158:159], off offset:384
	global_load_dwordx4 v[240:243], v[158:159], off offset:416
	global_load_dwordx4 v[244:247], v[158:159], off offset:448
	global_load_dwordx4 v[248:251], v[158:159], off offset:480
	v_fmac_f32_e32 v3, v73, v73
	v_fmac_f32_e32 v3, v74, v74
	v_fmac_f32_e32 v3, v75, v75
	v_fmac_f32_e32 v3, v76, v76
	v_fmac_f32_e32 v3, v77, v77
	v_fmac_f32_e32 v3, v78, v78
	v_fmac_f32_e32 v3, v79, v79
	v_fmac_f32_e32 v3, v48, v48
	v_fmac_f32_e32 v3, v49, v49
	v_fmac_f32_e32 v3, v50, v50
	v_fmac_f32_e32 v3, v51, v51
	v_fmac_f32_e32 v3, v52, v52
	v_fmac_f32_e32 v3, v53, v53
	v_fmac_f32_e32 v3, v54, v54
	v_fmac_f32_e32 v3, v55, v55
	v_fmac_f32_e32 v3, v56, v56
	v_fmac_f32_e32 v3, v57, v57
	v_fmac_f32_e32 v3, v58, v58
	v_fmac_f32_e32 v3, v59, v59
	v_fmac_f32_e32 v3, v60, v60
	v_fmac_f32_e32 v3, v61, v61
	v_fmac_f32_e32 v3, v62, v62
	v_fmac_f32_e32 v3, v63, v63
	s_waitcnt lgkmcnt(3)
	v_fma_f32 v32, v32, v2, -v4
	v_fmac_f32_e32 v3, v32, v32
	v_fma_f32 v33, v33, v2, -v5
	v_fmac_f32_e32 v3, v33, v33
	s_waitcnt lgkmcnt(2)
	v_fma_f32 v34, v34, v2, -v6
	v_fmac_f32_e32 v3, v34, v34
	v_fma_f32 v35, v35, v2, -v7
	ds_read2st64_b32 v[4:5], v1 offset0:40 offset1:41
	v_fmac_f32_e32 v3, v35, v35
	s_waitcnt lgkmcnt(2)
	v_fma_f32 v36, v36, v2, -v8
	v_fmac_f32_e32 v3, v36, v36
	v_fma_f32 v37, v37, v2, -v9
	v_fmac_f32_e32 v3, v37, v37
	s_waitcnt lgkmcnt(1)
	v_fma_f32 v38, v38, v2, -v10
	v_fmac_f32_e32 v3, v38, v38
	v_fma_f32 v39, v39, v2, -v11
	ds_read2st64_b32 v[6:7], v1 offset0:42 offset1:43
	ds_read2st64_b32 v[8:9], v1 offset0:44 offset1:45
	ds_read2st64_b32 v[10:11], v1 offset0:46 offset1:47
	v_fmac_f32_e32 v3, v39, v39
	s_waitcnt lgkmcnt(3)
	v_fma_f32 v40, v40, v2, -v4
	v_fmac_f32_e32 v3, v40, v40
	v_fma_f32 v41, v41, v2, -v5
	v_fmac_f32_e32 v3, v41, v41
	s_waitcnt lgkmcnt(2)
	v_fma_f32 v42, v42, v2, -v6
	v_fmac_f32_e32 v3, v42, v42
	v_fma_f32 v43, v43, v2, -v7
	ds_read2st64_b32 v[4:5], v1 offset0:48 offset1:49
	v_fmac_f32_e32 v3, v43, v43
	s_waitcnt lgkmcnt(2)
	v_fma_f32 v44, v44, v2, -v8
	v_fmac_f32_e32 v3, v44, v44
	v_fma_f32 v45, v45, v2, -v9
	v_fmac_f32_e32 v3, v45, v45
	s_waitcnt lgkmcnt(1)
	v_fma_f32 v46, v46, v2, -v10
	v_fmac_f32_e32 v3, v46, v46
	v_fma_f32 v47, v47, v2, -v11
	ds_read2st64_b32 v[6:7], v1 offset0:50 offset1:51
	ds_read2st64_b32 v[8:9], v1 offset0:52 offset1:53
	ds_read2st64_b32 v[10:11], v1 offset0:54 offset1:55
	v_fmac_f32_e32 v3, v47, v47
	s_waitcnt lgkmcnt(3)
	v_fma_f32 v80, v16, v2, -v4
	v_fmac_f32_e32 v3, v80, v80
	v_fma_f32 v81, v17, v2, -v5
	v_fmac_f32_e32 v3, v81, v81
	s_waitcnt lgkmcnt(2)
	v_fma_f32 v82, v18, v2, -v6
	v_fmac_f32_e32 v3, v82, v82
	v_fma_f32 v83, v19, v2, -v7
	v_fmac_f32_e32 v3, v83, v83
	s_waitcnt lgkmcnt(1)
	v_fma_f32 v20, v20, v2, -v8
	v_fmac_f32_e32 v3, v20, v20
	v_fma_f32 v21, v21, v2, -v9
	v_fmac_f32_e32 v3, v21, v21
	ds_read2st64_b32 v[6:7], v1 offset0:56 offset1:57
	s_waitcnt lgkmcnt(1)
	v_pk_fma_f32 v[10:11], v[22:23], v[2:3], v[10:11] op_sel_hi:[1,0,1] neg_lo:[0,0,1] neg_hi:[0,0,1]
	s_mulk_i32 s39, 0x2200
	v_pk_mul_f32 v[4:5], v[10:11], v[10:11]
	s_or_b32 s22, s37, s38
	v_add_f32_e32 v3, v3, v4
	v_add_f32_e32 v3, v3, v5
	ds_read2st64_b32 v[4:5], v1 offset0:58 offset1:59
	ds_read2st64_b32 v[16:17], v1 offset0:60 offset1:61
	ds_read_b32 v18, v1 offset:15872
	s_waitcnt lgkmcnt(3)
	v_pk_fma_f32 v[8:9], v[24:25], v[2:3], v[6:7] op_sel_hi:[1,0,1] neg_lo:[0,0,1] neg_hi:[0,0,1]
	s_ashr_i32 s23, s22, 31
	v_pk_mul_f32 v[6:7], v[8:9], v[8:9]
	s_lshl_b64 s[22:23], s[22:23], 12
	v_add_f32_e32 v1, v3, v6
	v_add_f32_e32 v1, v1, v7
	s_waitcnt lgkmcnt(2)
	v_pk_fma_f32 v[6:7], v[26:27], v[2:3], v[4:5] op_sel_hi:[1,0,1] neg_lo:[0,0,1] neg_hi:[0,0,1]
	v_add_u32_e32 v3, s4, v197
	ds_read_b32 v19, v3
	v_pk_mul_f32 v[4:5], v[6:7], v[6:7]
	s_add_i32 s4, s39, 0
	v_add_f32_e32 v1, v1, v4
	v_add_f32_e32 v1, v1, v5
	s_waitcnt lgkmcnt(2)
; __device__ __forceinline__ unsigned cvt_pk_bf16(float lo, float hi) { unsigned r; asm volatile("v_cvt_pk_bf16_f32 %0, %1, %2" : "=v"(r) : "v"(lo), "v"(hi)); return r; }
; #define ATT_LAS __attribute__((address_space(3)))
; __device__ __forceinline__ void diff_unit(ATT_LAS unsigned char* lds, int b, int h, int qb, const bf16_t* __restrict__ DQ, const bf16_t* __restrict__ DK, const bf16_t* __restrict__ VT,
;                                           float lam, const float* __restrict__ gout, bf16_t* __restrict__ MIXED) {
;     ...
;         ss += __shfl_xor(ss, 32);
;         const float rstd = rsqrtf(ss * (1.0f / 128.0f) + EPS) * 0.8f;
;         ATT_LAS unsigned char* stg = lds + 65536 + wq * OSTG_BYTES;
; #pragma unroll
;         for (int e = 0; e < 4; ++e)
; #pragma unroll
;             for (int g4 = 0; g4 < 4; ++g4) { const int e0 = 32 * e + 8 * g4 + 4 * hh; const f32x4 g = *(const f32x4*)(gout + e0);
;                 u32x2 w; w.x = cvt_pk_bf16(O[e][4 * g4] * rstd * g[0], O[e][4 * g4 + 1] * rstd * g[1]); w.y = cvt_pk_bf16(O[e][4 * g4 + 2] * rstd * g[2], O[e][4 * g4 + 3] * rstd * g[3]);
;                 *(ATT_LAS u32x2*)(stg + r * OSTG_PITCH + e0 * 2) = w; }
	v_pk_fma_f32 v[4:5], v[28:29], v[2:3], v[16:17] op_sel_hi:[1,0,1] neg_lo:[0,0,1] neg_hi:[0,0,1]
	s_waitcnt lgkmcnt(0)
	v_pk_fma_f32 v[2:3], v[30:31], v[2:3], v[18:19] op_sel_hi:[1,0,1] neg_lo:[0,0,1] neg_hi:[0,0,1]
	v_pk_mul_f32 v[16:17], v[4:5], v[4:5]
	s_add_i32 s4, s4, 0x10000
	v_add_f32_e32 v1, v1, v16
	v_add_f32_e32 v1, v1, v17
	v_pk_mul_f32 v[16:17], v[2:3], v[2:3]
	v_add_u32_e32 v18, s4, v198
	v_add_f32_e32 v1, v1, v16
	v_add_f32_e32 v1, v1, v17
	s_mov_b32 s98, -1
	s_mov_b32 s99, 0
	v_mov_b32_e32 v16, v1
	v_mov_b32_e32 v253, v1
	s_nop 1
	v_permlane32_swap_b32_e32 v16, v253
	v_cndmask_b32_e64 v16, v16, v253, s[98:99]
	v_add_u32_e32 v19, v18, v156
	s_add_u32 s22, s90, s22
	v_add3_u32 v30, s4, v191, v214
	s_addc_u32 s4, s91, s23
	s_waitcnt lgkmcnt(0)
	v_add_f32_e32 v1, v1, v16
	v_fmamk_f32 v1, v1, 0x3c000000, v216
	v_mul_f32_e32 v16, 0x4b800000, v1
	v_cmp_gt_f32_e32 vcc, s35, v1
	s_lshl_b32 s23, s36, 1
	s_add_u32 s22, s22, s23
	v_cndmask_b32_e32 v1, v1, v16, vcc
	v_rsq_f32_e32 v1, v1
	v_mov_b32_e32 v161, v0
	s_addc_u32 s23, s4, 0
	v_mov_b32_e32 v167, v0
	v_mul_f32_e32 v16, 0x45800000, v1
	v_cndmask_b32_e32 v1, v1, v16, vcc
	v_mul_f32_e32 v1, 0x3f4ccccd, v1
	v_mul_f32_e32 v16, v64, v1
	s_waitcnt vmcnt(0)
	v_mul_f32_e32 v12, v112, v16
	v_mul_f32_e32 v16, v65, v1
	v_mul_f32_e32 v13, v113, v16
	v_cvt_pk_bf16_f32 v16, v12, v13
	v_mul_f32_e32 v12, v66, v1
	v_mul_f32_e32 v13, v67, v1
	v_mul_f32_e32 v12, v114, v12
	v_mul_f32_e32 v13, v115, v13
	v_cvt_pk_bf16_f32 v17, v12, v13
	ds_write_b64 v19, v[16:17]
	v_mul_f32_e32 v16, v68, v1
	v_mul_f32_e32 v22, v72, v1
	v_mul_f32_e32 v23, v73, v1
	v_mul_f32_e32 v24, v74, v1
	v_mul_f32_e32 v25, v75, v1
	v_add_u32_e32 v19, v18, v199
	v_mul_f32_e32 v20, v20, v1
	v_mul_f32_e32 v21, v21, v1
	v_mul_f32_e32 v10, v10, v1
	v_mul_f32_e32 v11, v11, v1
	v_mul_f32_e32 v8, v8, v1
	v_mul_f32_e32 v9, v9, v1
	v_mul_f32_e32 v6, v6, v1
	v_mul_f32_e32 v7, v7, v1
	v_mul_f32_e32 v4, v4, v1
	v_mul_f32_e32 v5, v5, v1
	v_mul_f32_e32 v2, v2, v1
	v_mov_b32_e32 v169, v0
	v_mov_b32_e32 v171, v0
	v_mov_b32_e32 v173, v0
	v_mov_b32_e32 v175, v0
	v_mov_b32_e32 v177, v0
	v_mov_b32_e32 v179, v0
	v_mov_b32_e32 v181, v0
	v_mul_f32_e32 v12, v116, v16
	v_mul_f32_e32 v16, v69, v1
	v_mul_f32_e32 v13, v117, v16
	v_cvt_pk_bf16_f32 v16, v12, v13
	v_mul_f32_e32 v12, v70, v1
	v_mul_f32_e32 v13, v71, v1
	v_mul_f32_e32 v12, v118, v12
	v_mul_f32_e32 v13, v119, v13
	v_cvt_pk_bf16_f32 v17, v12, v13
	ds_write_b64 v19, v[16:17]
	v_add_u32_e32 v19, v18, v200
	v_mul_f32_e32 v12, v120, v22
	v_mul_f32_e32 v13, v121, v23
	v_mul_f32_e32 v14, v122, v24
	v_mul_f32_e32 v15, v123, v25
	v_cvt_pk_bf16_f32 v16, v12, v13
	v_cvt_pk_bf16_f32 v17, v14, v15
	v_mul_f32_e32 v22, v76, v1
	v_mul_f32_e32 v23, v77, v1
	v_mul_f32_e32 v24, v78, v1
	v_mul_f32_e32 v25, v79, v1
	ds_write_b64 v19, v[16:17]
	v_add_u32_e32 v19, v18, v201
	v_mul_f32_e32 v12, v22, v124
	v_mul_f32_e32 v13, v23, v125
	v_mul_f32_e32 v14, v24, v126
	v_mul_f32_e32 v15, v25, v127
	v_cvt_pk_bf16_f32 v16, v12, v13
	v_cvt_pk_bf16_f32 v17, v14, v15
	v_mul_f32_e32 v22, v48, v1
	v_mul_f32_e32 v23, v49, v1
	v_mul_f32_e32 v24, v50, v1
	v_mul_f32_e32 v25, v51, v1
	ds_write_b64 v19, v[16:17]
	v_add_u32_e32 v19, v18, v202
	v_mul_f32_e32 v12, v22, v128
	v_mul_f32_e32 v13, v23, v129
	v_mul_f32_e32 v14, v24, v130
	v_mul_f32_e32 v15, v25, v131
	v_cvt_pk_bf16_f32 v16, v12, v13
	v_cvt_pk_bf16_f32 v17, v14, v15
	v_mul_f32_e32 v22, v52, v1
	v_mul_f32_e32 v23, v53, v1
	v_mul_f32_e32 v24, v54, v1
	v_mul_f32_e32 v25, v55, v1
	ds_write_b64 v19, v[16:17]
	v_add_u32_e32 v19, v18, v203
	v_mul_f32_e32 v12, v22, v132
	v_mul_f32_e32 v13, v23, v133
	v_mul_f32_e32 v14, v24, v134
	v_mul_f32_e32 v15, v25, v135
	v_cvt_pk_bf16_f32 v16, v12, v13
	v_cvt_pk_bf16_f32 v17, v14, v15
	v_mul_f32_e32 v22, v56, v1
	v_mul_f32_e32 v23, v57, v1
	v_mul_f32_e32 v24, v58, v1
	v_mul_f32_e32 v25, v59, v1
	ds_write_b64 v19, v[16:17]
	v_add_u32_e32 v19, v18, v204
	v_mul_f32_e32 v12, v22, v136
	v_mul_f32_e32 v13, v23, v137
	v_mul_f32_e32 v14, v24, v138
	v_mul_f32_e32 v15, v25, v139
	v_cvt_pk_bf16_f32 v16, v12, v13
	v_cvt_pk_bf16_f32 v17, v14, v15
	v_mul_f32_e32 v22, v60, v1
	v_mul_f32_e32 v23, v61, v1
; __device__ __forceinline__ unsigned cvt_pk_bf16(float lo, float hi) { unsigned r; asm volatile("v_cvt_pk_bf16_f32 %0, %1, %2" : "=v"(r) : "v"(lo), "v"(hi)); return r; }
; #define ATT_LAS __attribute__((address_space(3)))
; __device__ __forceinline__ void diff_unit(ATT_LAS unsigned char* lds, int b, int h, int qb, const bf16_t* __restrict__ DQ, const bf16_t* __restrict__ DK, const bf16_t* __restrict__ VT,
;                                           float lam, const float* __restrict__ gout, bf16_t* __restrict__ MIXED) {
;     ...
;             for (int g4 = 0; g4 < 4; ++g4) { const int e0 = 32 * e + 8 * g4 + 4 * hh; const f32x4 g = *(const f32x4*)(gout + e0);
;                 u32x2 w; w.x = cvt_pk_bf16(O[e][4 * g4] * rstd * g[0], O[e][4 * g4 + 1] * rstd * g[1]); w.y = cvt_pk_bf16(O[e][4 * g4 + 2] * rstd * g[2], O[e][4 * g4 + 3] * rstd * g[3]);
;                 *(ATT_LAS u32x2*)(stg + r * OSTG_PITCH + e0 * 2) = w; }
;         asm volatile("s_waitcnt lgkmcnt(0)" ::: "memory");
;         bf16_t* obase = MIXED + (size_t)(b * 4096 + t0w) * 2048 + h * 128;
; #pragma unroll
;         for (int i = 0; i < 8; ++i) { const int c = lane + 64 * i, row = c >> 4, c16 = c & 15;
;             *(u32x4*)(obase + (size_t)row * 2048 + c16 * 8) = *(const ATT_LAS u32x4*)(stg + row * OSTG_PITCH + c16 * 16); }
;     }
;     __syncthreads();
	v_mul_f32_e32 v24, v62, v1
	v_mul_f32_e32 v25, v63, v1
	ds_write_b64 v19, v[16:17]
	v_add_u32_e32 v19, v18, v205
	v_mul_f32_e32 v12, v22, v140
	v_mul_f32_e32 v13, v23, v141
	v_mul_f32_e32 v14, v24, v142
	v_mul_f32_e32 v15, v25, v143
	v_cvt_pk_bf16_f32 v16, v12, v13
	v_cvt_pk_bf16_f32 v17, v14, v15
	v_mul_f32_e32 v22, v32, v1
	v_mul_f32_e32 v23, v33, v1
	v_mul_f32_e32 v24, v34, v1
	v_mul_f32_e32 v25, v35, v1
	ds_write_b64 v19, v[16:17]
	v_add_u32_e32 v19, v18, v206
	v_mul_f32_e32 v12, v22, v218
	v_mul_f32_e32 v13, v23, v219
	v_mul_f32_e32 v14, v24, v220
	v_mul_f32_e32 v15, v25, v221
	v_cvt_pk_bf16_f32 v16, v12, v13
	v_cvt_pk_bf16_f32 v17, v14, v15
	v_mul_f32_e32 v22, v36, v1
	v_mul_f32_e32 v23, v37, v1
	v_mul_f32_e32 v24, v38, v1
	v_mul_f32_e32 v25, v39, v1
	ds_write_b64 v19, v[16:17]
	v_add_u32_e32 v19, v18, v207
	v_mul_f32_e32 v12, v22, v222
	v_mul_f32_e32 v13, v23, v223
	v_mul_f32_e32 v14, v24, v224
	v_mul_f32_e32 v15, v25, v225
	v_cvt_pk_bf16_f32 v16, v12, v13
	v_cvt_pk_bf16_f32 v17, v14, v15
	v_mul_f32_e32 v22, v40, v1
	v_mul_f32_e32 v23, v41, v1
	v_mul_f32_e32 v24, v42, v1
	v_mul_f32_e32 v25, v43, v1
	ds_write_b64 v19, v[16:17]
	v_add_u32_e32 v19, v18, v208
	v_mul_f32_e32 v12, v22, v226
	v_mul_f32_e32 v13, v23, v227
	v_mul_f32_e32 v14, v24, v228
	v_mul_f32_e32 v15, v25, v229
	v_cvt_pk_bf16_f32 v16, v12, v13
	v_cvt_pk_bf16_f32 v17, v14, v15
	v_mul_f32_e32 v22, v44, v1
	v_mul_f32_e32 v23, v45, v1
	v_mul_f32_e32 v24, v46, v1
	v_mul_f32_e32 v25, v47, v1
	ds_write_b64 v19, v[16:17]
	v_add_u32_e32 v19, v18, v209
	v_mul_f32_e32 v12, v22, v230
	v_mul_f32_e32 v13, v23, v231
	v_mul_f32_e32 v14, v24, v232
	v_mul_f32_e32 v15, v25, v233
	v_cvt_pk_bf16_f32 v16, v12, v13
	v_cvt_pk_bf16_f32 v17, v14, v15
	v_mul_f32_e32 v22, v80, v1
	v_mul_f32_e32 v23, v81, v1
	v_mul_f32_e32 v24, v82, v1
	v_mul_f32_e32 v25, v83, v1
	ds_write_b64 v19, v[16:17]
	v_add_u32_e32 v19, v18, v210
	v_mul_f32_e32 v1, v3, v1
	v_mul_f32_e32 v12, v22, v234
	v_mul_f32_e32 v13, v23, v235
	v_mul_f32_e32 v14, v24, v236
	v_mul_f32_e32 v15, v25, v237
	v_cvt_pk_bf16_f32 v16, v12, v13
	v_cvt_pk_bf16_f32 v17, v14, v15
	ds_write_b64 v19, v[16:17]
	v_add_u32_e32 v16, v18, v211
	v_mul_f32_e32 v12, v20, v240
	v_mul_f32_e32 v13, v21, v241
	v_mul_f32_e32 v10, v10, v242
	v_mul_f32_e32 v11, v11, v243
	v_cvt_pk_bf16_f32 v14, v12, v13
	v_cvt_pk_bf16_f32 v15, v10, v11
	ds_write_b64 v16, v[14:15]
	v_add_u32_e32 v14, v18, v212
	v_add_u32_e32 v15, v18, v213
	v_mul_f32_e32 v8, v8, v244
	v_mul_f32_e32 v9, v9, v245
	v_mul_f32_e32 v6, v6, v246
	v_mul_f32_e32 v7, v7, v247
	v_cvt_pk_bf16_f32 v10, v8, v9
	v_cvt_pk_bf16_f32 v11, v6, v7
	ds_write_b64 v14, v[10:11]
	v_lshl_add_u64 v[12:13], s[22:23], 0, v[160:161]
	v_lshl_add_u64 v[34:35], v[12:13], 0, v[166:167]
	v_lshl_add_u64 v[36:37], v[12:13], 0, v[168:169]
	v_lshl_add_u64 v[38:39], v[12:13], 0, v[170:171]
	v_lshl_add_u64 v[40:41], v[12:13], 0, v[172:173]
	v_lshl_add_u64 v[42:43], v[12:13], 0, v[174:175]
	v_lshl_add_u64 v[44:45], v[12:13], 0, v[176:177]
	v_lshl_add_u64 v[46:47], v[12:13], 0, v[178:179]
	v_lshl_add_u64 v[48:49], v[12:13], 0, v[180:181]
	v_mul_f32_e32 v3, v4, v248
	v_mul_f32_e32 v4, v5, v249
	v_mul_f32_e32 v5, v2, v250
	v_mul_f32_e32 v1, v1, v251
	v_cvt_pk_bf16_f32 v2, v3, v4
	v_cvt_pk_bf16_f32 v3, v5, v1
	ds_write_b64 v15, v[2:3]
	s_waitcnt lgkmcnt(0)
	ds_read_b128 v[2:5], v30
	ds_read_b128 v[6:9], v30 offset:1088
	ds_read_b128 v[10:13], v30 offset:2176
	ds_read_b128 v[14:17], v30 offset:3264
	ds_read_b128 v[18:21], v30 offset:4352
	ds_read_b128 v[22:25], v30 offset:5440
	ds_read_b128 v[26:29], v30 offset:6528
	ds_read_b128 v[30:33], v30 offset:7616
	s_waitcnt lgkmcnt(7)
	global_store_dwordx4 v[34:35], v[2:5], off
	s_waitcnt lgkmcnt(6)
	global_store_dwordx4 v[36:37], v[6:9], off
	s_waitcnt lgkmcnt(5)
	global_store_dwordx4 v[38:39], v[10:13], off
	s_waitcnt lgkmcnt(4)
	global_store_dwordx4 v[40:41], v[14:17], off
	s_waitcnt lgkmcnt(3)
	global_store_dwordx4 v[42:43], v[18:21], off
	s_waitcnt lgkmcnt(2)
	global_store_dwordx4 v[44:45], v[22:25], off
	s_waitcnt lgkmcnt(1)
	global_store_dwordx4 v[46:47], v[26:29], off
	s_waitcnt lgkmcnt(0)
	global_store_dwordx4 v[48:49], v[30:33], off
	s_branch .LBB0_527
